# v62 + epilogue-start s_waitcnt vmcnt(0) removed in the load-free in-proj epilogue branches (v, qb/kb, vb/gates): no drain of the next unit's prefetched LDS-DMA pieces
# speedup vs baseline: 1.0004x; 1.0004x over previous
; __device__ __forceinline__ v4u pack8(const f32x4 a, const f32x4 b) { v4u w; w.x = pk2(a[0], a[1]); w.y = pk2(a[2], a[3]); w.z = pk2(b[0], b[1]); w.w = pk2(b[2], b[3]); return w; }
; __device__ __forceinline__ float silu_f(float x) { return x * __builtin_amdgcn_rcpf(1.0f + fast_exp(-x)); }
;     __device__ __forceinline__ void operator()(const f32x4 (&acc)[2][2][4][2], const pg8::Unit& u, int wr, int wc, int fr, int fq) const {
;     ...
;         } else if (pn < 14) {
;             bf16* dst = (bf16*)(ws + (pn < 10 ? WS_VB : (pn < 12 ? WS_GA : WS_GB))); const bool act = pn >= 10;
;             const int cb = 256 * (pn & 1) + 64 * wc + 8 * tt.p;
; #pragma unroll
;             for (int ai = 0; ai < 2; ++ai)
; #pragma unroll
;                 for (int m = 0; m < 4; ++m) {
;                     const int rowa = 256 * pm + 128 * ai + 64 * wr + 16 * m + tt.rr;
;                     const float rs = rs8[ai][m];
;                     v4u pk[2];
; #pragma unroll
;                     for (int bj = 0; bj < 2; ++bj) {
;                         f32x4 a = acc[ai][bj][m][0] * rs, b = acc[ai][bj][m][1] * rs;
;                         if (act) {
; #pragma unroll
;                             for (int j = 0; j < 4; ++j) { a[j] = silu_f(a[j]); b[j] = silu_f(b[j]); }
;                         }
;                         pk[bj] = pack8(a, b);
.LBB0_419:
	s_andn2_b64 vcc, exec, s[6:7]
	s_cbranch_vccnz .LBB0_453
	s_cmp_gt_u32 s42, 9
	s_cselect_b64 s[44:45], -1, 0
	s_cmp_lt_u32 s42, 10
	v_pk_mul_f32 v[130:131], v[128:129], v[162:163] op_sel_hi:[1,0]
	v_pk_mul_f32 v[132:133], v[126:127], v[162:163] op_sel_hi:[1,0]
	v_pk_mul_f32 v[134:135], v[124:125], v[162:163] op_sel_hi:[1,0]
	v_pk_mul_f32 v[136:137], v[122:123], v[162:163] op_sel_hi:[1,0]
	s_cbranch_scc1 .LBB0_422
	v_mul_f32_e32 v139, 0xbfb8aa3b, v136
	v_mul_f32_e32 v140, 0xbfb8aa3b, v133
	v_exp_f32_e32 v139, v139
	v_exp_f32_e32 v141, v140
	v_mul_f32_e32 v143, 0xbfb8aa3b, v134
	v_mul_f32_e32 v144, 0xbfb8aa3b, v131
	v_add_f32_e32 v139, 1.0, v139
	v_mul_f32_e32 v138, 0xbfb8aa3b, v132
	v_rcp_f32_e32 v140, v139
	v_add_f32_e32 v139, 1.0, v141
	v_mul_f32_e32 v141, 0xbfb8aa3b, v137
	v_mul_f32_e32 v142, 0xbfb8aa3b, v130
	v_exp_f32_e32 v143, v143
	v_exp_f32_e32 v145, v144
	v_mul_f32_e32 v144, 0xbfb8aa3b, v135
	v_exp_f32_e32 v138, v138
	v_exp_f32_e32 v141, v141
	v_exp_f32_e32 v142, v142
	v_exp_f32_e32 v146, v144
	v_add_f32_e32 v143, 1.0, v143
	v_add_f32_e32 v138, 1.0, v138
	v_add_f32_e32 v141, 1.0, v141
	v_add_f32_e32 v142, 1.0, v142
	v_rcp_f32_e32 v144, v143
	v_add_f32_e32 v143, 1.0, v145
	v_add_f32_e32 v145, 1.0, v146
	v_rcp_f32_e32 v138, v138
	v_rcp_f32_e32 v139, v139
	v_rcp_f32_e32 v142, v142
	v_rcp_f32_e32 v143, v143
	v_rcp_f32_e32 v145, v145
	v_rcp_f32_e32 v141, v141
	v_pk_mul_f32 v[132:133], v[132:133], v[138:139]
	v_pk_mul_f32 v[130:131], v[130:131], v[142:143]
	v_pk_mul_f32 v[134:135], v[134:135], v[144:145]
	v_pk_mul_f32 v[136:137], v[136:137], v[140:141]

; __device__ __forceinline__ v4u pack8(const f32x4 a, const f32x4 b) { v4u w; w.x = pk2(a[0], a[1]); w.y = pk2(a[2], a[3]); w.z = pk2(b[0], b[1]); w.w = pk2(b[2], b[3]); return w; }
;     __device__ __forceinline__ void operator()(const f32x4 (&acc)[2][2][4][2], const pg8::Unit& u, int wr, int wc, int fr, int fq) const {
;     ...
;         } else if (pn < 8) {
;             bf16* dst = (bf16*)(ws + (pn == 6 ? WS_QB : WS_KB)); const float sc = pn == 6 ? 0.125f : 1.0f;
; #pragma unroll
;             for (int ai = 0; ai < 2; ++ai)
; #pragma unroll
;                 for (int m = 0; m < 4; ++m) {
;                     const int rowa = 256 * pm + 128 * ai + 64 * wr + 16 * m + tt.rr;
;                     const float rs = rs8[ai][m] * sc;
;                     v4u a, b; tt.bf(pack8(acc[ai][0][m][0] * rs, acc[ai][0][m][1] * rs), pack8(acc[ai][1][m][0] * rs, acc[ai][1][m][1] * rs), a, b);
;                     bf16* d = dst + (size_t)rowa * 256 + wc * 64 + 8 * tt.p; *(v4u*)d = a; *(v4u*)(d + 8 * 256) = b;
;                 }
.LBB0_454:
	s_andn2_b64 vcc, exec, s[6:7]
	s_cbranch_vccnz .LBB0_456
	s_cmp_eq_u32 s42, 6
	s_cselect_b64 vcc, -1, 0
	v_cndmask_b32_e32 v150, 1.0, v223, vcc
	v_mul_f32_e32 v138, v150, v162
	s_and_b64 s[0:1], vcc, exec
	v_pk_mul_f32 v[136:137], v[128:129], v[138:139] op_sel_hi:[1,0]
	v_pk_mul_f32 v[134:135], v[126:127], v[138:139] op_sel_hi:[1,0]
	v_pk_mul_f32 v[140:141], v[124:125], v[138:139] op_sel_hi:[1,0]
	v_pk_mul_f32 v[142:143], v[122:123], v[138:139] op_sel_hi:[1,0]
	s_mov_b32 s0, 0x16c00000
	v_add_u32_e32 v151, s77, v229
	v_cvt_pk_bf16_f32 v134, v134, v135
	v_cvt_pk_bf16_f32 v135, v136, v137
	v_cvt_pk_bf16_f32 v136, v142, v143
	v_cvt_pk_bf16_f32 v137, v140, v141
	v_pk_mul_f32 v[140:141], v[120:121], v[138:139] op_sel_hi:[1,0]
	v_pk_mul_f32 v[142:143], v[118:119], v[138:139] op_sel_hi:[1,0]
	v_pk_mul_f32 v[144:145], v[116:117], v[138:139] op_sel_hi:[1,0]
	v_pk_mul_f32 v[146:147], v[114:115], v[138:139] op_sel_hi:[1,0]
	s_cselect_b32 s0, s0, 0x18e00000
	s_add_i32 s1, s9, s66
	v_add_u32_e32 v152, s77, v228
	v_add_u32_e32 v153, s77, v230
	v_cvt_pk_bf16_f32 v138, v142, v143
	v_cvt_pk_bf16_f32 v139, v140, v141
	v_cvt_pk_bf16_f32 v140, v146, v147
	v_cvt_pk_bf16_f32 v141, v144, v145
	ds_write_b128 v151, v[134:137]
	ds_write_b128 v152, v[138:141]
	v_add_u32_e32 v132, s1, v227
	s_add_u32 s0, s73, s0
	ds_read_b128 v[134:137], v153
	ds_read_b128 v[138:141], v153 offset:1024
	s_addc_u32 s1, s74, 0
	v_lshlrev_b32_e32 v184, 4, v213
	v_ashrrev_i32_e32 v133, 31, v132
	v_lshl_add_u64 v[130:131], s[0:1], 0, v[184:185]
	v_lshlrev_b64 v[142:143], 9, v[132:133]
	v_lshl_add_u64 v[142:143], v[130:131], 0, v[142:143]
	s_waitcnt lgkmcnt(1)
	global_store_dwordx4 v[142:143], v[134:137], off
	s_nop 1
	v_add_co_u32_e32 v134, vcc, s92, v142
	v_add_u32_e32 v142, 16, v132
	s_nop 0
	v_addc_co_u32_e32 v135, vcc, 0, v143, vcc
	s_waitcnt lgkmcnt(0)
	global_store_dwordx4 v[134:135], v[138:141], off
	v_ashrrev_i32_e32 v143, 31, v142
	v_lshlrev_b64 v[142:143], 9, v[142:143]
	v_mul_f32_e32 v138, v150, v210
	v_pk_mul_f32 v[136:137], v[112:113], v[138:139] op_sel_hi:[1,0]
	v_pk_mul_f32 v[134:135], v[110:111], v[138:139] op_sel_hi:[1,0]
	v_pk_mul_f32 v[140:141], v[108:109], v[138:139] op_sel_hi:[1,0]
	v_pk_mul_f32 v[144:145], v[106:107], v[138:139] op_sel_hi:[1,0]
	v_cvt_pk_bf16_f32 v134, v134, v135
	v_cvt_pk_bf16_f32 v135, v136, v137
	v_cvt_pk_bf16_f32 v136, v144, v145
	v_cvt_pk_bf16_f32 v137, v140, v141
	v_pk_mul_f32 v[140:141], v[104:105], v[138:139] op_sel_hi:[1,0]
	v_pk_mul_f32 v[144:145], v[102:103], v[138:139] op_sel_hi:[1,0]
	v_pk_mul_f32 v[146:147], v[100:101], v[138:139] op_sel_hi:[1,0]
	v_pk_mul_f32 v[148:149], v[98:99], v[138:139] op_sel_hi:[1,0]
	v_cvt_pk_bf16_f32 v138, v144, v145
	v_cvt_pk_bf16_f32 v139, v140, v141
	v_cvt_pk_bf16_f32 v140, v148, v149
	v_cvt_pk_bf16_f32 v141, v146, v147
	ds_write_b128 v151, v[134:137]
	ds_write_b128 v152, v[138:141]
	ds_read_b128 v[134:137], v153
	ds_read_b128 v[138:141], v153 offset:1024
	v_lshl_add_u64 v[142:143], v[130:131], 0, v[142:143]
	s_waitcnt lgkmcnt(1)
	global_store_dwordx4 v[142:143], v[134:137], off
	s_nop 1
	v_add_co_u32_e32 v134, vcc, s92, v142
	v_add_u32_e32 v142, 32, v132
	s_nop 0
	v_addc_co_u32_e32 v135, vcc, 0, v143, vcc
	s_waitcnt lgkmcnt(0)
	global_store_dwordx4 v[134:135], v[138:141], off
	v_ashrrev_i32_e32 v143, 31, v142
	v_lshlrev_b64 v[142:143], 9, v[142:143]
	v_mul_f32_e32 v138, v150, v208
	v_pk_mul_f32 v[136:137], v[96:97], v[138:139] op_sel_hi:[1,0]
	v_pk_mul_f32 v[134:135], v[94:95], v[138:139] op_sel_hi:[1,0]
	v_pk_mul_f32 v[140:141], v[92:93], v[138:139] op_sel_hi:[1,0]
	v_pk_mul_f32 v[144:145], v[90:91], v[138:139] op_sel_hi:[1,0]
	v_cvt_pk_bf16_f32 v134, v134, v135
	v_cvt_pk_bf16_f32 v135, v136, v137
	v_cvt_pk_bf16_f32 v136, v144, v145
	v_cvt_pk_bf16_f32 v137, v140, v141
	v_pk_mul_f32 v[140:141], v[88:89], v[138:139] op_sel_hi:[1,0]
	v_pk_mul_f32 v[144:145], v[86:87], v[138:139] op_sel_hi:[1,0]
	v_pk_mul_f32 v[146:147], v[84:85], v[138:139] op_sel_hi:[1,0]
	v_pk_mul_f32 v[148:149], v[82:83], v[138:139] op_sel_hi:[1,0]
	v_cvt_pk_bf16_f32 v138, v144, v145
	v_cvt_pk_bf16_f32 v139, v140, v141
	v_cvt_pk_bf16_f32 v140, v148, v149
	v_cvt_pk_bf16_f32 v141, v146, v147
	ds_write_b128 v151, v[134:137]
	ds_write_b128 v152, v[138:141]
	ds_read_b128 v[134:137], v153
	ds_read_b128 v[138:141], v153 offset:1024
	v_lshl_add_u64 v[142:143], v[130:131], 0, v[142:143]
	s_waitcnt lgkmcnt(1)
	global_store_dwordx4 v[142:143], v[134:137], off
	s_nop 1
	v_add_co_u32_e32 v134, vcc, s92, v142
	v_add_u32_e32 v142, 48, v132
	s_nop 0
	v_addc_co_u32_e32 v135, vcc, 0, v143, vcc
	s_waitcnt lgkmcnt(0)
	global_store_dwordx4 v[134:135], v[138:141], off
	v_ashrrev_i32_e32 v143, 31, v142
	v_lshlrev_b64 v[142:143], 9, v[142:143]
	v_mul_f32_e32 v138, v150, v206
	v_pk_mul_f32 v[136:137], v[80:81], v[138:139] op_sel_hi:[1,0]
	v_pk_mul_f32 v[134:135], v[78:79], v[138:139] op_sel_hi:[1,0]
	v_pk_mul_f32 v[140:141], v[76:77], v[138:139] op_sel_hi:[1,0]
	v_pk_mul_f32 v[144:145], v[74:75], v[138:139] op_sel_hi:[1,0]
	v_cvt_pk_bf16_f32 v134, v134, v135
	v_cvt_pk_bf16_f32 v135, v136, v137
	v_cvt_pk_bf16_f32 v136, v144, v145
	v_cvt_pk_bf16_f32 v137, v140, v141
	v_pk_mul_f32 v[140:141], v[72:73], v[138:139] op_sel_hi:[1,0]
	v_pk_mul_f32 v[144:145], v[70:71], v[138:139] op_sel_hi:[1,0]
	v_pk_mul_f32 v[146:147], v[68:69], v[138:139] op_sel_hi:[1,0]
	v_pk_mul_f32 v[148:149], v[66:67], v[138:139] op_sel_hi:[1,0]
	v_cvt_pk_bf16_f32 v138, v144, v145
	v_cvt_pk_bf16_f32 v139, v140, v141
	v_cvt_pk_bf16_f32 v140, v148, v149
	v_cvt_pk_bf16_f32 v141, v146, v147
	ds_write_b128 v151, v[134:137]
	ds_write_b128 v152, v[138:141]
	ds_read_b128 v[134:137], v153
	ds_read_b128 v[138:141], v153 offset:1024
	v_lshl_add_u64 v[142:143], v[130:131], 0, v[142:143]
	s_waitcnt lgkmcnt(1)
; __device__ __forceinline__ v4u pack8(const f32x4 a, const f32x4 b) { v4u w; w.x = pk2(a[0], a[1]); w.y = pk2(a[2], a[3]); w.z = pk2(b[0], b[1]); w.w = pk2(b[2], b[3]); return w; }
;     __device__ __forceinline__ void operator()(const f32x4 (&acc)[2][2][4][2], const pg8::Unit& u, int wr, int wc, int fr, int fq) const {
;     ...
; #pragma unroll
;             for (int ai = 0; ai < 2; ++ai)
; #pragma unroll
;                 for (int m = 0; m < 4; ++m) {
;                     const int rowa = 256 * pm + 128 * ai + 64 * wr + 16 * m + tt.rr;
;                     const float rs = rs8[ai][m] * sc;
;                     v4u a, b; tt.bf(pack8(acc[ai][0][m][0] * rs, acc[ai][0][m][1] * rs), pack8(acc[ai][1][m][0] * rs, acc[ai][1][m][1] * rs), a, b);
;                     bf16* d = dst + (size_t)rowa * 256 + wc * 64 + 8 * tt.p; *(v4u*)d = a; *(v4u*)(d + 8 * 256) = b;
;                 }
	global_store_dwordx4 v[142:143], v[134:137], off
	s_nop 1
	v_add_co_u32_e32 v134, vcc, s92, v142
	v_add_u32_e32 v142, 0x80, v132
	s_nop 0
	v_addc_co_u32_e32 v135, vcc, 0, v143, vcc
	s_waitcnt lgkmcnt(0)
	global_store_dwordx4 v[134:135], v[138:141], off
	v_ashrrev_i32_e32 v143, 31, v142
	v_lshlrev_b64 v[142:143], 9, v[142:143]
	v_mul_f32_e32 v138, v150, v204
	v_pk_mul_f32 v[136:137], v[64:65], v[138:139] op_sel_hi:[1,0]
	v_pk_mul_f32 v[134:135], v[62:63], v[138:139] op_sel_hi:[1,0]
	v_pk_mul_f32 v[140:141], v[60:61], v[138:139] op_sel_hi:[1,0]
	v_pk_mul_f32 v[144:145], v[58:59], v[138:139] op_sel_hi:[1,0]
	v_cvt_pk_bf16_f32 v134, v134, v135
	v_cvt_pk_bf16_f32 v135, v136, v137
	v_cvt_pk_bf16_f32 v136, v144, v145
	v_cvt_pk_bf16_f32 v137, v140, v141
	v_pk_mul_f32 v[140:141], v[56:57], v[138:139] op_sel_hi:[1,0]
	v_pk_mul_f32 v[144:145], v[54:55], v[138:139] op_sel_hi:[1,0]
	v_pk_mul_f32 v[146:147], v[52:53], v[138:139] op_sel_hi:[1,0]
	v_pk_mul_f32 v[148:149], v[50:51], v[138:139] op_sel_hi:[1,0]
	v_cvt_pk_bf16_f32 v138, v144, v145
	v_cvt_pk_bf16_f32 v139, v140, v141
	v_cvt_pk_bf16_f32 v140, v148, v149
	v_cvt_pk_bf16_f32 v141, v146, v147
	ds_write_b128 v151, v[134:137]
	ds_write_b128 v152, v[138:141]
	ds_read_b128 v[134:137], v153
	ds_read_b128 v[138:141], v153 offset:1024
	v_lshl_add_u64 v[142:143], v[130:131], 0, v[142:143]
	s_waitcnt lgkmcnt(1)
	global_store_dwordx4 v[142:143], v[134:137], off
	s_nop 1
	v_add_co_u32_e32 v134, vcc, s92, v142
	v_add_u32_e32 v142, 0x90, v132
	s_nop 0
	v_addc_co_u32_e32 v135, vcc, 0, v143, vcc
	s_waitcnt lgkmcnt(0)
	global_store_dwordx4 v[134:135], v[138:141], off
	v_ashrrev_i32_e32 v143, 31, v142
	v_lshlrev_b64 v[142:143], 9, v[142:143]
	v_mul_f32_e32 v138, v150, v202
	v_pk_mul_f32 v[136:137], v[48:49], v[138:139] op_sel_hi:[1,0]
	v_pk_mul_f32 v[134:135], v[46:47], v[138:139] op_sel_hi:[1,0]
	v_pk_mul_f32 v[140:141], v[44:45], v[138:139] op_sel_hi:[1,0]
	v_pk_mul_f32 v[144:145], v[42:43], v[138:139] op_sel_hi:[1,0]
	v_cvt_pk_bf16_f32 v134, v134, v135
	v_cvt_pk_bf16_f32 v135, v136, v137
	v_cvt_pk_bf16_f32 v136, v144, v145
	v_cvt_pk_bf16_f32 v137, v140, v141
	v_pk_mul_f32 v[140:141], v[40:41], v[138:139] op_sel_hi:[1,0]
	v_pk_mul_f32 v[144:145], v[38:39], v[138:139] op_sel_hi:[1,0]
	v_pk_mul_f32 v[146:147], v[36:37], v[138:139] op_sel_hi:[1,0]
	v_pk_mul_f32 v[148:149], v[34:35], v[138:139] op_sel_hi:[1,0]
	v_cvt_pk_bf16_f32 v138, v144, v145
	v_cvt_pk_bf16_f32 v139, v140, v141
	v_cvt_pk_bf16_f32 v140, v148, v149
	v_cvt_pk_bf16_f32 v141, v146, v147
	ds_write_b128 v151, v[134:137]
	ds_write_b128 v152, v[138:141]
	ds_read_b128 v[134:137], v153
	ds_read_b128 v[138:141], v153 offset:1024
	v_lshl_add_u64 v[142:143], v[130:131], 0, v[142:143]
	s_waitcnt lgkmcnt(1)
	global_store_dwordx4 v[142:143], v[134:137], off
	s_nop 1
	v_add_co_u32_e32 v134, vcc, s92, v142
	v_add_u32_e32 v142, 0xa0, v132
	s_nop 0
	v_addc_co_u32_e32 v135, vcc, 0, v143, vcc
	s_waitcnt lgkmcnt(0)
	global_store_dwordx4 v[134:135], v[138:141], off
	v_ashrrev_i32_e32 v143, 31, v142
	v_lshlrev_b64 v[142:143], 9, v[142:143]
	v_mul_f32_e32 v138, v150, v198
	v_pk_mul_f32 v[136:137], v[32:33], v[138:139] op_sel_hi:[1,0]
	v_pk_mul_f32 v[134:135], v[30:31], v[138:139] op_sel_hi:[1,0]
	v_pk_mul_f32 v[140:141], v[28:29], v[138:139] op_sel_hi:[1,0]
	v_pk_mul_f32 v[144:145], v[26:27], v[138:139] op_sel_hi:[1,0]
	v_cvt_pk_bf16_f32 v134, v134, v135
	v_cvt_pk_bf16_f32 v135, v136, v137
	v_cvt_pk_bf16_f32 v136, v144, v145
	v_cvt_pk_bf16_f32 v137, v140, v141
	v_pk_mul_f32 v[140:141], v[24:25], v[138:139] op_sel_hi:[1,0]
	v_pk_mul_f32 v[144:145], v[22:23], v[138:139] op_sel_hi:[1,0]
	v_pk_mul_f32 v[146:147], v[20:21], v[138:139] op_sel_hi:[1,0]
	v_pk_mul_f32 v[148:149], v[18:19], v[138:139] op_sel_hi:[1,0]
	v_cvt_pk_bf16_f32 v138, v144, v145
	v_cvt_pk_bf16_f32 v139, v140, v141
	v_cvt_pk_bf16_f32 v140, v148, v149
	v_cvt_pk_bf16_f32 v141, v146, v147
	ds_write_b128 v151, v[134:137]
	ds_write_b128 v152, v[138:141]
	ds_read_b128 v[134:137], v153
	ds_read_b128 v[138:141], v153 offset:1024
	v_lshl_add_u64 v[142:143], v[130:131], 0, v[142:143]
	s_waitcnt lgkmcnt(1)
	global_store_dwordx4 v[142:143], v[134:137], off
	s_nop 1
	v_add_co_u32_e32 v134, vcc, s92, v142
	v_mul_f32_e32 v136, v150, v196
	s_nop 0
	v_addc_co_u32_e32 v135, vcc, 0, v143, vcc
	s_waitcnt lgkmcnt(0)
	global_store_dwordx4 v[134:135], v[138:141], off
	v_pk_mul_f32 v[134:135], v[16:17], v[136:137] op_sel_hi:[1,0]
	v_pk_mul_f32 v[142:143], v[10:11], v[136:137] op_sel_hi:[1,0]
	v_add_u32_e32 v140, 0xb0, v132
	v_pk_mul_f32 v[132:133], v[14:15], v[136:137] op_sel_hi:[1,0]
	v_pk_mul_f32 v[138:139], v[12:13], v[136:137] op_sel_hi:[1,0]
	v_cvt_pk_bf16_f32 v132, v132, v133
	v_cvt_pk_bf16_f32 v133, v134, v135
	v_cvt_pk_bf16_f32 v134, v142, v143
	v_cvt_pk_bf16_f32 v135, v138, v139
	v_pk_mul_f32 v[138:139], v[8:9], v[136:137] op_sel_hi:[1,0]
	v_pk_mul_f32 v[142:143], v[6:7], v[136:137] op_sel_hi:[1,0]
	v_pk_mul_f32 v[144:145], v[4:5], v[136:137] op_sel_hi:[1,0]
	v_pk_mul_f32 v[146:147], v[2:3], v[136:137] op_sel_hi:[1,0]
	v_cvt_pk_bf16_f32 v136, v142, v143
	v_cvt_pk_bf16_f32 v137, v138, v139
	v_cvt_pk_bf16_f32 v138, v146, v147
	v_cvt_pk_bf16_f32 v139, v144, v145
	ds_write_b128 v151, v[132:135]
	ds_write_b128 v152, v[136:139]
	ds_read_b128 v[132:135], v153
	ds_read_b128 v[136:139], v153 offset:1024
	v_ashrrev_i32_e32 v141, 31, v140
	v_lshlrev_b64 v[140:141], 9, v[140:141]
	v_lshl_add_u64 v[130:131], v[130:131], 0, v[140:141]
	s_waitcnt lgkmcnt(1)
	global_store_dwordx4 v[130:131], v[132:135], off
	v_add_co_u32_e32 v130, vcc, 0x1000, v130
	s_nop 1
	v_addc_co_u32_e32 v131, vcc, 0, v131, vcc
	s_waitcnt lgkmcnt(0)
	global_store_dwordx4 v[130:131], v[136:139], off

; __device__ __forceinline__ v4u pack8(const f32x4 a, const f32x4 b) { v4u w; w.x = pk2(a[0], a[1]); w.y = pk2(a[2], a[3]); w.z = pk2(b[0], b[1]); w.w = pk2(b[2], b[3]); return w; }
;     __device__ __forceinline__ void operator()(const f32x4 (&acc)[2][2][4][2], const pg8::Unit& u, int wr, int wc, int fr, int fq) const {
;     ...
;         } else if (pn < 6) {
;             const int head = 4 * (pn & 1) + wc;
;             const bool wout = sample || (pm & 15) >= 8;
; #pragma unroll
;             for (int ai = 0; ai < 2; ++ai)
; #pragma unroll
;                 for (int m = 0; m < 4; ++m) {
;                     const int rl = 128 * ai + 64 * wr + 16 * m + tt.rr, rowa = 256 * pm + rl;
;                     const float rs = rs8[ai][m];
;                     const f32x4 a0 = acc[ai][0][m][0] * rs, a1 = acc[ai][0][m][1] * rs, b0 = acc[ai][1][m][0] * rs, b1 = acc[ai][1][m][1] * rs;
;                     { v4u a, b; tt.bf(pack8(a0, a1), pack8(b0, b1), a, b);
;                       bf16* d = (bf16*)(ws + WS_V) + (size_t)rowa * DA + head * 64 + 8 * tt.p; *(v4u*)d = a; *(v4u*)(d + 8 * DA) = b; }
;                     if (wout) {
;                         float* op = sample ? out + OUT_VNEW + (size_t)(rowa - MP) * DA : out + OUT_VWIN + ((size_t)(pm >> 4) * WIN + (256 * (pm & 15) + rl - (SEQ - WIN))) * DA;
;                         op += head * 64 + 4 * tt.p;
;                         f32x4 a, b; tt.f4(a0, a1, a, b); *(f32x4*)op = a; *(f32x4*)(op + 8 * DA) = b;
;                         tt.f4(b0, b1, a, b); *(f32x4*)(op + 32) = a; *(f32x4*)(op + 32 + 8 * DA) = b;
;                     }
.LBB0_457:
	s_andn2_b64 vcc, exec, s[6:7]
	s_cbranch_vccnz .LBB0_474
	s_lshl_b32 s0, s42, 2
	v_add_u32_e32 v153, s66, v227
	v_pk_mul_f32 v[140:141], v[128:129], v[162:163] op_sel_hi:[1,0]
	v_pk_mul_f32 v[138:139], v[126:127], v[162:163] op_sel_hi:[1,0]
	v_pk_mul_f32 v[144:145], v[124:125], v[162:163] op_sel_hi:[1,0]
	v_pk_mul_f32 v[142:143], v[122:123], v[162:163] op_sel_hi:[1,0]
	s_and_b32 s0, s0, 4
	v_add_u32_e32 v151, s77, v229
	v_add_u32_e32 v148, s9, v153
	v_pk_mul_f32 v[132:133], v[120:121], v[162:163] op_sel_hi:[1,0]
	v_pk_mul_f32 v[130:131], v[118:119], v[162:163] op_sel_hi:[1,0]
	v_pk_mul_f32 v[136:137], v[116:117], v[162:163] op_sel_hi:[1,0]
	v_pk_mul_f32 v[134:135], v[114:115], v[162:163] op_sel_hi:[1,0]
	v_cvt_pk_bf16_f32 v154, v138, v139
	v_cvt_pk_bf16_f32 v155, v140, v141
	v_cvt_pk_bf16_f32 v156, v142, v143
	v_cvt_pk_bf16_f32 v157, v144, v145
	s_or_b32 s12, s0, s65
	s_and_b32 s0, s8, 15
	v_add_u32_e32 v152, s77, v228
	v_add_u32_e32 v150, s77, v230
	v_cvt_pk_bf16_f32 v164, v130, v131
	v_cvt_pk_bf16_f32 v165, v132, v133
	v_cvt_pk_bf16_f32 v166, v134, v135
	v_cvt_pk_bf16_f32 v167, v136, v137
	ds_write_b128 v151, v[154:157]
	ds_write_b128 v152, v[164:167]
	v_ashrrev_i32_e32 v149, 31, v148
	s_cmp_gt_u32 s0, 7
	ds_read_b128 v[154:157], v150
	ds_read_b128 v[164:167], v150 offset:1024
	v_lshlrev_b64 v[146:147], 10, v[148:149]
	s_cselect_b64 s[6:7], -1, 0
	s_lshl_b32 s1, s12, 6
	v_lshl_add_u64 v[146:147], s[26:27], 0, v[146:147]
	s_lshl_b32 s12, s12, 7
	v_lshl_add_u64 v[146:147], v[146:147], 0, s[12:13]
	v_lshlrev_b32_e32 v184, 4, v213
	v_lshl_add_u64 v[146:147], v[146:147], 0, v[184:185]
	s_waitcnt lgkmcnt(1)
	global_store_dwordx4 v[146:147], v[154:157], off
	v_add_co_u32_e32 v146, vcc, 0x2000, v146
	s_ashr_i32 s44, s8, 4
	s_nop 0
	v_addc_co_u32_e32 v147, vcc, 0, v147, vcc
	s_or_b64 s[46:47], s[4:5], s[6:7]
	s_ashr_i32 s45, s44, 31
	s_lshl_b32 s0, s0, 8
	v_lshl_or_b32 v160, v213, 2, s1
	s_waitcnt lgkmcnt(0)
	global_store_dwordx4 v[146:147], v[164:167], off
	v_cndmask_b32_e64 v146, 0, 1, s[46:47]
	s_addk_i32 s0, 0xf800
	s_lshl_b64 s[44:45], s[44:45], 22
	v_cmp_ne_u32_e64 s[6:7], 1, v146
	s_andn2_b64 vcc, exec, s[46:47]
	v_lshlrev_b32_e32 v146, 2, v160
	s_cbranch_vccnz .LBB0_460
	v_add_u32_e32 v154, s77, v226
	v_add_u32_e32 v155, s77, v225
	v_add_u32_e32 v147, s0, v153
	s_add_u32 s12, s78, s44
	v_add_u32_e32 v148, 0xffff0000, v148
	ds_write_b128 v154, v[138:141]
	ds_write_b128 v155, v[142:145]
	s_addc_u32 s33, s79, s45
	v_cndmask_b32_e64 v148, v147, v148, s[4:5]
	ds_read_b128 v[138:141], v150
	s_and_b64 s[46:47], s[4:5], exec
	v_ashrrev_i32_e32 v149, 31, v148
	s_cselect_b32 s47, s81, s33
	s_cselect_b32 s46, s80, s12
	v_lshlrev_b64 v[148:149], 11, v[148:149]
	v_lshl_add_u64 v[142:143], s[46:47], 0, v[148:149]
	v_mov_b32_e32 v147, v185
	v_lshl_add_u64 v[148:149], v[142:143], 0, v[146:147]
	ds_read_b128 v[142:145], v150 offset:1024
	s_waitcnt lgkmcnt(1)
	global_store_dwordx4 v[148:149], v[138:141], off nt
	ds_write_b128 v154, v[130:133]
	ds_write_b128 v155, v[134:137]
	ds_read_b128 v[130:133], v150
	ds_read_b128 v[134:137], v150 offset:1024
	v_add_co_u32_e32 v138, vcc, 0x4000, v148
	s_nop 1
	v_addc_co_u32_e32 v139, vcc, 0, v149, vcc
	s_waitcnt lgkmcnt(4)
	global_store_dwordx4 v[138:139], v[142:145], off nt
	s_waitcnt lgkmcnt(1)
	global_store_dwordx4 v[148:149], v[130:133], off offset:128 nt
	s_waitcnt lgkmcnt(0)
	global_store_dwordx4 v[138:139], v[134:137], off offset:128 nt
